# tile order remap W=8 for P7/P13/P9 (L2 locality), same math
# speedup vs baseline: 1.0036x; 1.0036x over previous
.LBB0_546:
	s_or_b64 exec, exec, s[6:7]
	s_cmpk_lt_i32 s33, 0xb00
	s_cselect_b64 s[4:5], -1, 0
	v_mov_b32_e32 v9, v242
	v_writelane_b32 v255, s4, 0
	s_waitcnt lgkmcnt(0)
	s_barrier
	v_writelane_b32 v255, s5, 1
	s_cmpk_gt_i32 s33, 0xaff
	v_readfirstlane_b32 s6, v9
	s_cbranch_scc1 .LBB0_562
	v_lshlrev_b32_e32 v0, 4, v9
	v_add_u32_e32 v1, 0x2000, v0
	v_ashrrev_i32_e32 v2, 31, v1
	v_lshrrev_b32_e32 v2, 22, v2
	v_add_u32_e32 v2, v1, v2
	v_ashrrev_i32_e32 v8, 10, v2
	v_mul_i32_i24_e32 v2, 0x400, v8
	v_sub_u32_e32 v1, v1, v2
	v_lshrrev_b32_e32 v2, 4, v1
	v_bitop3_b32 v1, v2, v1, 32 bitop3:0x6c
	v_ashrrev_i32_e32 v2, 31, v1
	v_lshrrev_b32_e32 v2, 26, v2
	v_add_u32_e32 v2, v1, v2
	v_lshlrev_b32_e32 v3, 3, v8
	v_ashrrev_i32_e32 v10, 6, v2
	v_and_b32_e32 v3, -16, v3
	v_add_u32_e32 v3, v10, v3
	v_and_b32_e32 v4, 3, v10
	s_mov_b32 s10, 0x1fffe0
	v_lshrrev_b32_e32 v5, 2, v3
	v_lshlrev_b32_e32 v6, 1, v3
	v_and_b32_e32 v2, 0xc0, v2
	v_and_or_b32 v4, v3, s10, v4
	v_and_b32_e32 v5, 4, v5
	v_and_b32_e32 v6, 24, v6
	v_sub_u32_e32 v1, v1, v2
	v_mov_b32_e32 v2, 1
	v_or3_b32 v4, v4, v5, v6
	v_lshlrev_b32_e32 v5, 5, v8
	v_ashrrev_i16_sdwa v1, v2, sext(v1) dst_sel:DWORD dst_unused:UNUSED_PAD src0_sel:DWORD src1_sel:BYTE_0
	v_and_b32_e32 v5, 32, v5
	v_bfe_i32 v11, v1, 0, 16
	v_add_lshl_u32 v1, v5, v11, 1
	v_lshl_add_u32 v128, v4, 11, v1
	v_lshl_add_u32 v130, v3, 11, v1
	v_bfe_i32 v1, v9, 27, 1
	v_lshrrev_b32_e32 v1, 22, v1
	v_add_u32_e32 v1, v0, v1
	v_and_b32_e32 v1, 0xfffffc00, v1
	v_sub_u32_e32 v0, v0, v1
	v_lshrrev_b32_e32 v1, 4, v0
	v_ashrrev_i32_e32 v3, 31, v9
	v_bitop3_b32 v0, v1, v0, 32 bitop3:0x6c
	v_lshrrev_b32_e32 v3, 26, v3
	v_ashrrev_i32_e32 v1, 31, v0
	v_add_u32_e32 v3, v9, v3
	v_lshrrev_b32_e32 v1, 26, v1
	v_ashrrev_i32_e32 v13, 6, v3
	v_add_u32_e32 v1, v0, v1
	v_lshlrev_b32_e32 v3, 3, v13
	s_add_u32 s4, s54, 0x1100000
	v_ashrrev_i32_e32 v12, 6, v1
	v_and_b32_e32 v3, -16, v3
	s_addc_u32 s5, s55, 0
	v_add_u32_e32 v3, v12, v3
	v_and_b32_e32 v4, 3, v12
	s_ashr_i32 s37, s33, 31
	v_and_or_b32 v4, v3, s10, v4
	s_lshr_b32 s10, s37, 29
	s_add_i32 s10, s33, s10
	s_ashr_i32 s12, s6, 6
	s_ashr_i32 s11, s10, 3
	s_and_b32 s10, s10, -8
	s_ashr_i32 s7, s6, 8
	s_lshl_b32 s36, s12, 10
	s_sub_i32 s10, s33, s10
	s_cmp_lt_i32 s10, 0
	s_movk_i32 s38, 0x161
	s_cselect_b32 s13, s38, 0x160
	s_mul_i32 s10, s10, s13
	s_add_i32 s10, s10, s11
	s_mul_i32 s11, s10, 5958
	s_lshr_b32 s11, s11, 20
	s_mul_i32 s13, s11, 176
	s_sub_i32 s13, s10, s13
	s_lshl_b32 s11, s11, 3
	v_lshrrev_b32_e32 v5, 2, v3
	v_lshlrev_b32_e32 v6, 1, v3
	v_and_b32_e32 v1, 0xc0, v1
	s_and_b32 s26, s13, 7
	s_add_i32 s26, s26, s11
	s_lshr_b32 s24, s13, 3
	v_and_b32_e32 v5, 4, v5
	v_and_b32_e32 v6, 24, v6
	v_sub_u32_e32 v0, v0, v1
	s_ashr_i32 s27, s26, 31
	s_ashr_i32 s25, s24, 31
	v_or3_b32 v4, v4, v5, v6
	v_lshlrev_b32_e32 v5, 5, v13
	v_ashrrev_i16_sdwa v0, v2, sext(v0) dst_sel:DWORD dst_unused:UNUSED_PAD src0_sel:DWORD src1_sel:BYTE_0
	s_lshl_b64 s[10:11], s[26:27], 19
	s_lshl_b64 s[14:15], s[24:25], 19
	v_and_b32_e32 v5, 32, v5
	v_bfe_i32 v14, v0, 0, 16
	s_add_u32 s30, s4, s14
	v_add_lshl_u32 v0, v5, v14, 1
	s_addc_u32 s31, s5, s15
	s_add_i32 s25, s36, 0
	v_lshl_add_u32 v132, v4, 11, v0
	s_add_i32 m0, s25, 0x10000
	v_lshl_add_u32 v134, v3, 11, v0
	global_load_lds_dwordx4 v132, s[30:31]
	s_add_i32 m0, s25, 0x12000
	s_add_u32 s14, s30, 0x40000
	global_load_lds_dwordx4 v128, s[30:31]
	s_addc_u32 s15, s31, 0
	s_add_i32 m0, s25, 0x14000
	v_mov_b32_e32 v133, 0
	global_load_lds_dwordx4 v132, s[14:15]
	s_add_i32 m0, s25, 0x16000
	s_add_u32 s28, s58, s10
	s_addc_u32 s29, s59, s11
	s_add_i32 s27, s25, 0x2000
	global_load_lds_dwordx4 v128, s[14:15]
	s_mov_b32 m0, s25
	s_add_u32 s10, s28, 0x40000
	global_load_lds_dwordx4 v134, s[28:29]
	s_mov_b32 m0, s27
	s_addc_u32 s11, s29, 0
	s_add_i32 s39, s25, 0x4000
	global_load_lds_dwordx4 v130, s[28:29]
	s_mov_b32 m0, s39
	s_add_i32 s40, s25, 0x6000
	global_load_lds_dwordx4 v134, s[10:11]
	s_mov_b32 m0, s40
	v_mov_b32_e32 v129, v133
	global_load_lds_dwordx4 v130, s[10:11]
	v_mov_b32_e32 v135, v133
	v_mov_b32_e32 v131, v133
	s_cmp_eq_u32 s7, 1
	s_mov_b32 s41, 0
	v_lshl_add_u64 v[6:7], s[30:31], 0, v[132:133]
	v_lshl_add_u64 v[4:5], s[30:31], 0, v[128:129]
	v_lshl_add_u64 v[0:1], s[28:29], 0, v[134:135]
	s_cselect_b64 s[10:11], -1, 0
	s_cmp_lg_u32 s7, 1
	v_lshl_add_u64 v[2:3], s[28:29], 0, v[130:131]
	s_cbranch_scc1 .LBB0_549
	s_barrier

.LBB0_552:
	s_add_i32 s41, s41, 1
	s_mul_i32 s6, s41, s46
	s_mul_hi_u32 s7, s41, s47
	s_add_i32 s7, s7, s6
	s_mul_i32 s6, s41, s47
	s_add_u32 s20, s6, s33
	s_addc_u32 s21, s7, s37
	v_cmp_gt_i64_e32 vcc, s[20:21], v[142:143]
	v_cmp_lt_i64_e64 s[6:7], s[20:21], v[140:141]
	s_cbranch_vccnz .LBB0_554
	s_ashr_i32 s16, s20, 31
	s_lshr_b32 s16, s16, 29
	s_add_i32 s16, s20, s16
	s_ashr_i32 s17, s16, 3
	s_and_b32 s16, s16, -8
	s_sub_i32 s16, s20, s16
	s_cmp_lt_i32 s16, 0
	s_cselect_b32 s18, s38, 0x160
	s_mul_i32 s16, s16, s18
	s_add_i32 s16, s16, s17
	s_mul_i32 s17, s16, 5958
	s_lshr_b32 s17, s17, 20
	s_mul_i32 s18, s17, 176
	s_sub_i32 s20, s16, s18
	s_lshl_b32 s17, s17, 3
	s_and_b32 s18, s20, 7
	s_add_i32 s18, s18, s17
	s_lshr_b32 s16, s20, 3

.LBB0_712:
	s_or_b64 exec, exec, s[6:7]
	v_mov_b32_e32 v8, v242
	s_cmpk_lt_i32 s33, 0x900
	s_waitcnt lgkmcnt(0)
	s_barrier
	s_cselect_b64 s[6:7], -1, 0
	s_cmpk_gt_i32 s33, 0x8ff
	v_readfirstlane_b32 s16, v8
	s_cbranch_scc1 .LBB0_714
	s_ashr_i32 s4, s33, 31
	s_lshr_b32 s4, s4, 29
	s_add_i32 s4, s33, s4
	s_ashr_i32 s5, s4, 3
	s_and_b32 s4, s4, -8
	s_sub_i32 s4, s33, s4
	s_cmp_lt_i32 s4, 0
	s_movk_i32 s8, 0x121
	s_cselect_b32 s8, s8, 0x120
	s_mul_i32 s4, s4, s8
	s_add_i32 s4, s4, s5
	s_mul_i32 s5, s4, 7282
	s_lshr_b32 s5, s5, 20
	s_mul_i32 s8, s5, 144
	s_sub_i32 s50, s4, s8
	s_lshl_b32 s5, s5, 3
	s_and_b32 s8, s50, 7
	s_add_i32 s8, s8, s5
	s_lshr_b32 s50, s50, 3

.LBB0_720:
	s_add_i32 s73, s73, 1
	s_mul_i32 s6, s73, s84
	s_mul_hi_u32 s7, s73, s85
	s_add_i32 s7, s7, s6
	s_mul_i32 s6, s73, s85
	s_add_u32 s42, s6, s33
	s_addc_u32 s43, s7, s86
	v_mov_b64_e32 v[0:1], 0x900
	v_cmp_lt_i64_e64 s[6:7], s[42:43], v[0:1]
	v_mov_b64_e32 v[0:1], 0x8ff
	v_cmp_gt_i64_e32 vcc, s[42:43], v[0:1]
	s_cbranch_vccnz .LBB0_722
	s_ashr_i32 s9, s42, 31
	s_lshr_b32 s9, s9, 29
	s_add_i32 s9, s42, s9
	s_ashr_i32 s38, s9, 3
	s_and_b32 s9, s9, -8
	s_sub_i32 s9, s42, s9
	s_cmp_lt_i32 s9, 0
	s_cselect_b32 s39, s87, 0x120
	s_mul_i32 s9, s9, s39
	s_add_i32 s9, s9, s38
	s_mul_i32 s38, s9, 7282
	s_lshr_b32 s38, s38, 20
	s_mul_i32 s39, s38, 144
	s_sub_i32 s39, s9, s39
	s_lshl_b32 s38, s38, 3
	s_and_b32 s40, s39, 7
	s_add_i32 s40, s40, s38
	s_lshr_b32 s38, s39, 3

.LBB0_1184:
	s_or_b64 exec, exec, s[6:7]
	v_readlane_b32 s4, v255, 0
	v_mov_b32_e32 v9, v242
	v_readlane_b32 s5, v255, 1
	s_waitcnt lgkmcnt(0)
	s_barrier
	s_andn2_b64 vcc, exec, s[4:5]
	v_readfirstlane_b32 s6, v9
	s_cbranch_vccnz .LBB0_1200
	v_lshlrev_b32_e32 v0, 4, v9
	v_add_u32_e32 v1, 0x2000, v0
	v_ashrrev_i32_e32 v2, 31, v1
	v_lshrrev_b32_e32 v2, 22, v2
	v_add_u32_e32 v2, v1, v2
	v_ashrrev_i32_e32 v8, 10, v2
	v_mul_i32_i24_e32 v2, 0x400, v8
	v_sub_u32_e32 v1, v1, v2
	v_lshrrev_b32_e32 v2, 4, v1
	v_bitop3_b32 v1, v2, v1, 32 bitop3:0x6c
	v_ashrrev_i32_e32 v2, 31, v1
	v_lshrrev_b32_e32 v2, 26, v2
	v_add_u32_e32 v2, v1, v2
	v_lshlrev_b32_e32 v3, 3, v8
	v_ashrrev_i32_e32 v10, 6, v2
	v_and_b32_e32 v3, -16, v3
	v_add_u32_e32 v3, v10, v3
	v_and_b32_e32 v4, 3, v10
	s_mov_b32 s10, 0x1fffe0
	v_lshrrev_b32_e32 v5, 2, v3
	v_lshlrev_b32_e32 v6, 1, v3
	v_and_b32_e32 v2, 0xc0, v2
	v_and_or_b32 v4, v3, s10, v4
	v_and_b32_e32 v5, 4, v5
	v_and_b32_e32 v6, 24, v6
	v_sub_u32_e32 v1, v1, v2
	v_mov_b32_e32 v2, 1
	v_or3_b32 v4, v4, v5, v6
	v_lshlrev_b32_e32 v5, 5, v8
	v_ashrrev_i16_sdwa v1, v2, sext(v1) dst_sel:DWORD dst_unused:UNUSED_PAD src0_sel:DWORD src1_sel:BYTE_0
	v_and_b32_e32 v5, 32, v5
	v_bfe_i32 v11, v1, 0, 16
	v_add_lshl_u32 v1, v5, v11, 1
	v_lshl_add_u32 v128, v4, 11, v1
	v_lshl_add_u32 v130, v3, 11, v1
	v_bfe_i32 v1, v9, 27, 1
	v_lshrrev_b32_e32 v1, 22, v1
	v_add_u32_e32 v1, v0, v1
	v_and_b32_e32 v1, 0xfffffc00, v1
	v_sub_u32_e32 v0, v0, v1
	v_lshrrev_b32_e32 v1, 4, v0
	v_ashrrev_i32_e32 v3, 31, v9
	v_bitop3_b32 v0, v1, v0, 32 bitop3:0x6c
	v_lshrrev_b32_e32 v3, 26, v3
	v_ashrrev_i32_e32 v1, 31, v0
	v_add_u32_e32 v3, v9, v3
	v_lshrrev_b32_e32 v1, 26, v1
	v_ashrrev_i32_e32 v13, 6, v3
	v_add_u32_e32 v1, v0, v1
	v_lshlrev_b32_e32 v3, 3, v13
	s_add_u32 s2, s54, 0x2d00000
	v_ashrrev_i32_e32 v12, 6, v1
	v_and_b32_e32 v3, -16, v3
	s_addc_u32 s4, s55, 0
	v_add_u32_e32 v3, v12, v3
	v_and_b32_e32 v4, 3, v12
	s_ashr_i32 s36, s33, 31
	v_and_or_b32 v4, v3, s10, v4
	s_lshr_b32 s10, s36, 29
	s_add_i32 s10, s33, s10
	s_ashr_i32 s12, s6, 6
	s_ashr_i32 s11, s10, 3
	s_and_b32 s10, s10, -8
	s_ashr_i32 s7, s6, 8
	s_lshl_b32 s5, s12, 10
	s_sub_i32 s10, s33, s10
	s_cmp_lt_i32 s10, 0
	s_movk_i32 s37, 0x161
	s_cselect_b32 s13, s37, 0x160
	s_mul_i32 s10, s10, s13
	s_add_i32 s10, s10, s11
	s_mul_i32 s11, s10, 5958
	s_lshr_b32 s11, s11, 20
	s_mul_i32 s13, s11, 176
	s_sub_i32 s13, s10, s13
	s_lshl_b32 s11, s11, 3
	v_lshrrev_b32_e32 v5, 2, v3
	v_lshlrev_b32_e32 v6, 1, v3
	v_and_b32_e32 v1, 0xc0, v1
	s_and_b32 s26, s13, 7
	s_add_i32 s26, s26, s11
	s_lshr_b32 s24, s13, 3
	v_and_b32_e32 v5, 4, v5
	v_and_b32_e32 v6, 24, v6
	v_sub_u32_e32 v0, v0, v1
	s_ashr_i32 s27, s26, 31
	s_ashr_i32 s25, s24, 31
	v_or3_b32 v4, v4, v5, v6
	v_lshlrev_b32_e32 v5, 5, v13
	v_ashrrev_i16_sdwa v0, v2, sext(v0) dst_sel:DWORD dst_unused:UNUSED_PAD src0_sel:DWORD src1_sel:BYTE_0
	s_lshl_b64 s[10:11], s[26:27], 19
	s_lshl_b64 s[14:15], s[24:25], 19
	v_and_b32_e32 v5, 32, v5
	v_bfe_i32 v14, v0, 0, 16
	s_add_u32 s30, s2, s14
	v_add_lshl_u32 v0, v5, v14, 1
	s_addc_u32 s31, s4, s15
	s_add_i32 s25, s5, 0
	v_lshl_add_u32 v132, v4, 11, v0
	s_add_i32 m0, s25, 0x10000
	v_lshl_add_u32 v134, v3, 11, v0
	global_load_lds_dwordx4 v132, s[30:31]
	s_add_i32 m0, s25, 0x12000
	s_add_u32 s14, s30, 0x40000
	global_load_lds_dwordx4 v128, s[30:31]
	s_addc_u32 s15, s31, 0
	s_add_i32 m0, s25, 0x14000
	v_mov_b32_e32 v133, 0
	global_load_lds_dwordx4 v132, s[14:15]
	s_add_i32 m0, s25, 0x16000
	s_add_u32 s28, s58, s10
	s_addc_u32 s29, s59, s11
	s_add_i32 s27, s25, 0x2000
	global_load_lds_dwordx4 v128, s[14:15]
	s_mov_b32 m0, s25
	s_add_u32 s10, s28, 0x40000
	global_load_lds_dwordx4 v134, s[28:29]
	s_mov_b32 m0, s27
	s_addc_u32 s11, s29, 0
	s_add_i32 s38, s25, 0x4000
	global_load_lds_dwordx4 v130, s[28:29]
	s_mov_b32 m0, s38
	s_add_i32 s39, s25, 0x6000
	global_load_lds_dwordx4 v134, s[10:11]
	s_mov_b32 m0, s39
	v_mov_b32_e32 v129, v133
	global_load_lds_dwordx4 v130, s[10:11]
	v_mov_b32_e32 v135, v133
	v_mov_b32_e32 v131, v133
	s_cmp_eq_u32 s7, 1
	s_mov_b32 s40, 0
	v_lshl_add_u64 v[6:7], s[30:31], 0, v[132:133]
	v_lshl_add_u64 v[4:5], s[30:31], 0, v[128:129]
	v_lshl_add_u64 v[0:1], s[28:29], 0, v[134:135]
	s_cselect_b64 s[10:11], -1, 0
	s_cmp_lg_u32 s7, 1
	v_lshl_add_u64 v[2:3], s[28:29], 0, v[130:131]
	s_cbranch_scc1 .LBB0_1187
	s_barrier

.LBB0_1190:
	s_add_i32 s40, s40, 1
	s_mul_i32 s6, s40, s43
	s_mul_hi_u32 s7, s40, s46
	s_add_i32 s7, s7, s6
	s_mul_i32 s6, s40, s46
	s_add_u32 s20, s6, s33
	s_addc_u32 s21, s7, s36
	v_cmp_gt_i64_e32 vcc, s[20:21], v[142:143]
	v_cmp_lt_i64_e64 s[6:7], s[20:21], v[140:141]
	s_cbranch_vccnz .LBB0_1192
	s_ashr_i32 s16, s20, 31
	s_lshr_b32 s16, s16, 29
	s_add_i32 s16, s20, s16
	s_ashr_i32 s17, s16, 3
	s_and_b32 s16, s16, -8
	s_sub_i32 s16, s20, s16
	s_cmp_lt_i32 s16, 0
	s_cselect_b32 s18, s37, 0x160
	s_mul_i32 s16, s16, s18
	s_add_i32 s16, s16, s17
	s_mul_i32 s17, s16, 5958
	s_lshr_b32 s17, s17, 20
	s_mul_i32 s18, s17, 176
	s_sub_i32 s20, s16, s18
	s_lshl_b32 s17, s17, 3
	s_and_b32 s18, s20, 7
	s_add_i32 s18, s18, s17
	s_lshr_b32 s16, s20, 3
